# residual-GEMM epilogues: 16-lane sum-of-squares butterfly via DPP row ops (quad_perm, row_half_mirror, row_mirror) instead of 4 ds_bpermute round trips per row piece
# speedup vs baseline: 1.0047x; 1.0047x over previous
; DI float hlo(unsigned u) { return h2f((bf16_t)(u & 0xffffu)); }
; DI float hhi(unsigned u) { return h2f((bf16_t)(u >> 16)); }
; DI int crow(int r, int h) { return (r & 3) + 8 * (r >> 2) + 4 * h; }
; DI void ph_res(KP p, const bf16_t* A, int K, const bf16_t* Wt, const float* xin, char* smem, bool dry) {
;     ...
;         float* stg = (float*)smem;
; #pragma unroll
;         for (int i = 0; i < 2; ++i)
; #pragma unroll
;             for (int j = 0; j < 2; ++j)
; #pragma unroll
;                 for (int r = 0; r < 16; ++r) stg[(wm * 64 + i * 32 + crow(r, h)) * 132 + wn * 64 + j * 32 + l32] = acc[i][j][r];
;         __syncthreads();
;         bf16_t* xb = (bf16_t*)(p->ws + OFF_XB) + (size_t)(rt * 128) * DM + ct * 128;
;         float* part = (float*)(p->ws + OFF_RSC) + (size_t)(rt * 128) * 16 + ct * 2;
;         const int c8 = tt & 15;
; #pragma unroll
;         for (int i = 0; i < 8; ++i) {
;             const int row = (tt >> 4) + 16 * i;
;             const float4 lo = *(const float4*)(stg + row * 132 + c8 * 8), hi = *(const float4*)(stg + row * 132 + c8 * 8 + 4);
;             uint4* gp = (uint4*)(xb + (size_t)row * DM + c8 * 8);
;             const uint4 xv = *gp;
;             uint4 nv;
;             nv.x = pack2h(hlo(xv.x) + lo.x, hhi(xv.x) + lo.y); nv.y = pack2h(hlo(xv.y) + lo.z, hhi(xv.y) + lo.w);
;             nv.z = pack2h(hlo(xv.z) + hi.x, hhi(xv.z) + hi.y); nv.w = pack2h(hlo(xv.w) + hi.z, hhi(xv.w) + hi.w);
;             *gp = nv;
;             float s0 = hlo(nv.x), s1 = hhi(nv.x), s2 = hlo(nv.y), s3 = hhi(nv.y), s4 = hlo(nv.z), s5 = hhi(nv.z), s6 = hlo(nv.w), s7 = hhi(nv.w);
;             float sq = s0 * s0 + s1 * s1 + s2 * s2 + s3 * s3 + s4 * s4 + s5 * s5 + s6 * s6 + s7 * s7;
;             sq += __shfl_xor(sq, 1); sq += __shfl_xor(sq, 2); sq += __shfl_xor(sq, 4); sq += __shfl_xor(sq, 8);
;             if (c8 == 0) { float2 pv; pv.x = sq; pv.y = 0.f; *(float2*)(part + (size_t)row * 16) = pv; }
;         }
.LBB0_37:
	v_mov_b32_e32 v32, v182
	s_ashr_i32 s37, s36, 31
	v_readfirstlane_b32 s13, v32
	s_lshr_b32 s34, s13, 1
	v_and_b32_e32 v33, 31, v32
	s_and_b32 s34, s34, 0xfffffc0
	v_lshrrev_b32_e32 v34, 3, v32
	v_and_or_b32 v34, v34, 4, s34
	v_and_or_b32 v33, s13, 64, v33
	v_mul_lo_u32 v34, v34, s82
	v_lshlrev_b32_e32 v33, 2, v33
	v_add3_u32 v33, 0, v34, v33
	v_add_u32_e32 v34, 0x400, v33
	ds_write2_b32 v33, v52, v36 offset1:32
	ds_write2_b32 v33, v53, v37 offset0:132 offset1:164
	ds_write2_b32 v34, v54, v38 offset0:8 offset1:40
	ds_write2_b32 v34, v55, v39 offset0:140 offset1:172
	v_add_u32_e32 v34, 0x1000, v33
	ds_write2_b32 v34, v56, v40 offset0:32 offset1:64
	ds_write2_b32 v34, v57, v41 offset0:164 offset1:196
	v_add_u32_e32 v34, 0x1400, v33
	ds_write2_b32 v34, v58, v42 offset0:40 offset1:72
	ds_write2_b32 v34, v59, v43 offset0:172 offset1:204
	v_add_u32_e32 v34, 0x2000, v33
	ds_write2_b32 v34, v60, v44 offset0:64 offset1:96
	ds_write2_b32 v34, v61, v45 offset0:196 offset1:228
	v_add_u32_e32 v34, 0x2400, v33
	ds_write2_b32 v34, v62, v46 offset0:72 offset1:104
	ds_write2_b32 v34, v63, v47 offset0:204 offset1:236
	v_add_u32_e32 v34, 0x3000, v33
	ds_write2_b32 v34, v64, v48 offset0:96 offset1:128
	v_add_u32_e32 v34, 0x3200, v33
	ds_write2_b32 v34, v65, v49 offset0:100 offset1:132
	v_add_u32_e32 v34, 0x3400, v33
	ds_write2_b32 v34, v66, v50 offset0:104 offset1:136
	v_add_u32_e32 v34, 0x3600, v33
	ds_write2_b32 v34, v67, v51 offset0:108 offset1:140
	v_add_u32_e32 v34, 0x4000, v33
	ds_write2_b32 v34, v16, v0 offset0:128 offset1:160
	v_add_u32_e32 v0, 0x4400, v33
	ds_write2_b32 v0, v17, v1 offset0:4 offset1:36
	ds_write2_b32 v0, v18, v2 offset0:136 offset1:168
	v_add_u32_e32 v0, 0x4800, v33
	ds_write2_b32 v0, v19, v3 offset0:12 offset1:44
	v_add_u32_e32 v0, 0x5000, v33
	ds_write2_b32 v0, v20, v4 offset0:160 offset1:192
	v_add_u32_e32 v0, 0x5400, v33
	ds_write2_b32 v0, v21, v5 offset0:36 offset1:68
	ds_write2_b32 v0, v22, v6 offset0:168 offset1:200
	v_add_u32_e32 v0, 0x5800, v33
	ds_write2_b32 v0, v23, v7 offset0:44 offset1:76
	v_add_u32_e32 v0, 0x6000, v33
	s_lshl_b64 s[34:35], s[36:37], 11
	ds_write2_b32 v0, v24, v8 offset0:192 offset1:224
	v_add_u32_e32 v0, 0x6400, v33
	s_add_u32 s13, s7, s34
	ds_write2_b32 v0, v25, v9 offset0:68 offset1:100
	ds_write2_b32 v0, v26, v10 offset0:200 offset1:232
	v_add_u32_e32 v0, 0x6800, v33
	s_addc_u32 s42, s8, s35
	s_lshl_b32 s34, s12, 7
	ds_write2_b32 v0, v27, v11 offset0:76 offset1:108
	v_add_u32_e32 v0, 0x7200, v33
	s_ashr_i32 s35, s34, 31
	ds_write2_b32 v0, v28, v12 offset0:96 offset1:128
	v_add_u32_e32 v0, 0x7400, v33
	s_lshl_b64 s[34:35], s[34:35], 1
	ds_write2_b32 v0, v29, v13 offset0:100 offset1:132
	v_add_u32_e32 v0, 0x7600, v33
	s_add_u32 s34, s13, s34
	v_and_b32_e32 v11, 15, v32
	v_ashrrev_i32_e32 v2, 4, v32
	ds_write2_b32 v0, v30, v14 offset0:104 offset1:136
	v_add_u32_e32 v0, 0x7800, v33
	s_addc_u32 s35, s42, s35
	v_lshlrev_b32_e32 v34, 4, v11
	v_ashrrev_i32_e32 v3, 31, v2
	ds_write2_b32 v0, v31, v15 offset0:108 offset1:140
	v_lshl_add_u64 v[0:1], s[34:35], 0, v[34:35]
	v_lshlrev_b64 v[4:5], 11, v[2:3]
	v_lshl_add_u64 v[24:25], v[0:1], 0, v[4:5]
	s_waitcnt lgkmcnt(0)
	s_barrier
	global_load_dwordx4 v[12:15], v[24:25], off
	v_cmp_lt_i32_e32 vcc, v186, v187
	v_lshl_add_u32 v4, v11, 5, 0
	s_lshl_b64 s[34:35], s[36:37], 6
	v_cndmask_b32_e32 v5, v184, v186, vcc
	v_lshlrev_b32_e32 v6, 2, v5
	v_mul_lo_u32 v5, v2, s82
	v_add_u32_e32 v10, v4, v5
	ds_read_b128 v[16:19], v10
	ds_read_b128 v[20:23], v10 offset:16
	v_cmp_lt_i32_e32 vcc, v188, v187
	s_add_u32 s34, s9, s34
	s_addc_u32 s35, s10, s35
	s_lshl_b32 s12, s12, 1
	s_ashr_i32 s13, s12, 31
	s_lshl_b64 s[12:13], s[12:13], 2
	s_add_u32 s36, s34, s12
	s_addc_u32 s37, s35, s13
	s_waitcnt vmcnt(0)
	v_cvt_f32_f16_e32 v4, v12
	v_cvt_f32_f16_sdwa v5, v12 dst_sel:DWORD dst_unused:UNUSED_PAD src0_sel:WORD_1
	v_cvt_f32_f16_e32 v8, v13
	v_cvt_f32_f16_sdwa v9, v13 dst_sel:DWORD dst_unused:UNUSED_PAD src0_sel:WORD_1
	s_waitcnt lgkmcnt(1)
	v_pk_add_f32 v[4:5], v[16:17], v[4:5]
	s_nop 0
	v_cvt_pk_f16_f32 v12, v4, v5
	v_pk_add_f32 v[4:5], v[18:19], v[8:9]
	v_cvt_f32_f16_sdwa v7, v12 dst_sel:DWORD dst_unused:UNUSED_PAD src0_sel:WORD_1
	v_cvt_pk_f16_f32 v13, v4, v5
	v_cvt_f32_f16_e32 v4, v15
	v_cvt_f32_f16_sdwa v5, v15 dst_sel:DWORD dst_unused:UNUSED_PAD src0_sel:WORD_1
	v_cvt_f32_f16_e32 v8, v14
	v_cvt_f32_f16_sdwa v9, v14 dst_sel:DWORD dst_unused:UNUSED_PAD src0_sel:WORD_1
	s_waitcnt lgkmcnt(0)
	v_pk_add_f32 v[4:5], v[22:23], v[4:5]
	s_nop 0
	v_cvt_pk_f16_f32 v15, v4, v5
	v_mul_f32_e32 v4, v7, v7
	v_fma_mix_f32 v4, v12, v12, v4 op_sel_hi:[1,1,0]
	v_pk_add_f32 v[8:9], v[20:21], v[8:9]
	v_fma_mix_f32 v4, v13, v13, v4 op_sel_hi:[1,1,0]
	v_cvt_pk_f16_f32 v14, v8, v9
	v_fma_mix_f32 v4, v13, v13, v4 op_sel:[1,1,0] op_sel_hi:[1,1,0]
	v_cndmask_b32_e32 v7, v184, v188, vcc
	v_fma_mix_f32 v4, v14, v14, v4 op_sel_hi:[1,1,0]
	v_lshlrev_b32_e32 v7, 2, v7
	v_fma_mix_f32 v4, v14, v14, v4 op_sel:[1,1,0] op_sel_hi:[1,1,0]
	v_cmp_lt_i32_e32 vcc, v189, v187
	v_fma_mix_f32 v4, v15, v15, v4 op_sel_hi:[1,1,0]
	global_store_dwordx4 v[24:25], v[12:15], off
	v_fma_mix_f32 v4, v15, v15, v4 op_sel:[1,1,0] op_sel_hi:[1,1,0]
	s_nop 1
	v_add_f32_dpp v4, v4, v4 quad_perm:[1,0,3,2] row_mask:0xf bank_mask:0xf
	v_cndmask_b32_e32 v8, v184, v189, vcc
	v_lshlrev_b32_e32 v8, 2, v8
	v_cmp_lt_i32_e32 vcc, v190, v187
	s_waitcnt lgkmcnt(0)
	s_nop 1
	v_add_f32_dpp v4, v4, v4 quad_perm:[2,3,0,1] row_mask:0xf bank_mask:0xf
	v_cndmask_b32_e32 v9, v184, v190, vcc
	v_lshlrev_b32_e32 v9, 2, v9
	v_cmp_eq_u32_e32 vcc, 0, v11
	s_waitcnt lgkmcnt(0)
	s_nop 1
	v_add_f32_dpp v4, v4, v4 row_half_mirror row_mask:0xf bank_mask:0xf
	s_waitcnt lgkmcnt(0)
	s_nop 1
	v_mov_b32_dpp v5, v4 row_mirror row_mask:0xf bank_mask:0xf
	s_and_saveexec_b64 s[42:43], vcc
	s_cbranch_execz .LBB0_39
	s_waitcnt lgkmcnt(0)
	v_add_f32_e32 v34, v4, v5
	v_lshlrev_b64 v[4:5], 6, v[2:3]
	v_lshl_add_u64 v[4:5], s[36:37], 0, v[4:5]
	global_store_dwordx2 v[4:5], v[34:35], off
; DI float hlo(unsigned u) { return h2f((bf16_t)(u & 0xffffu)); }
; DI float hhi(unsigned u) { return h2f((bf16_t)(u >> 16)); }
; DI void ph_res(KP p, const bf16_t* A, int K, const bf16_t* Wt, const float* xin, char* smem, bool dry) {
;     ...
;         for (int i = 0; i < 8; ++i) {
;             const int row = (tt >> 4) + 16 * i;
;             const float4 lo = *(const float4*)(stg + row * 132 + c8 * 8), hi = *(const float4*)(stg + row * 132 + c8 * 8 + 4);
;             uint4* gp = (uint4*)(xb + (size_t)row * DM + c8 * 8);
;             const uint4 xv = *gp;
;             uint4 nv;
;             nv.x = pack2h(hlo(xv.x) + lo.x, hhi(xv.x) + lo.y); nv.y = pack2h(hlo(xv.y) + lo.z, hhi(xv.y) + lo.w);
;             nv.z = pack2h(hlo(xv.z) + hi.x, hhi(xv.z) + hi.y); nv.w = pack2h(hlo(xv.w) + hi.z, hhi(xv.w) + hi.w);
;             *gp = nv;
;             float s0 = hlo(nv.x), s1 = hhi(nv.x), s2 = hlo(nv.y), s3 = hhi(nv.y), s4 = hlo(nv.z), s5 = hhi(nv.z), s6 = hlo(nv.w), s7 = hhi(nv.w);
;             float sq = s0 * s0 + s1 * s1 + s2 * s2 + s3 * s3 + s4 * s4 + s5 * s5 + s6 * s6 + s7 * s7;
;             sq += __shfl_xor(sq, 1); sq += __shfl_xor(sq, 2); sq += __shfl_xor(sq, 4); sq += __shfl_xor(sq, 8);
;             if (c8 == 0) { float2 pv; pv.x = sq; pv.y = 0.f; *(float2*)(part + (size_t)row * 16) = pv; }
.LBB0_39:
	s_or_b64 exec, exec, s[42:43]
	v_add_u32_e32 v4, 16, v2
	s_waitcnt lgkmcnt(0)
	v_ashrrev_i32_e32 v5, 31, v4
	v_lshlrev_b64 v[12:13], 11, v[4:5]
	v_lshl_add_u64 v[24:25], v[0:1], 0, v[12:13]
	global_load_dwordx4 v[12:15], v[24:25], off
	ds_read_b128 v[16:19], v10 offset:8448
	ds_read_b128 v[20:23], v10 offset:8464
	s_waitcnt vmcnt(0)
	v_cvt_f32_f16_e32 v26, v12
	v_cvt_f32_f16_sdwa v27, v12 dst_sel:DWORD dst_unused:UNUSED_PAD src0_sel:WORD_1
	s_waitcnt lgkmcnt(1)
	v_pk_add_f32 v[16:17], v[16:17], v[26:27]
	s_nop 0
	v_cvt_pk_f16_f32 v12, v16, v17
	v_cvt_f32_f16_e32 v16, v13
	v_cvt_f32_f16_sdwa v17, v13 dst_sel:DWORD dst_unused:UNUSED_PAD src0_sel:WORD_1
	v_cvt_f32_f16_sdwa v3, v12 dst_sel:DWORD dst_unused:UNUSED_PAD src0_sel:WORD_1
	v_pk_add_f32 v[16:17], v[18:19], v[16:17]
	s_nop 0
	v_cvt_pk_f16_f32 v13, v16, v17
	v_cvt_f32_f16_e32 v16, v14
	v_cvt_f32_f16_sdwa v17, v14 dst_sel:DWORD dst_unused:UNUSED_PAD src0_sel:WORD_1
	v_mul_f32_e32 v3, v3, v3
	v_fma_mix_f32 v3, v12, v12, v3 op_sel_hi:[1,1,0]
	s_waitcnt lgkmcnt(0)
	v_pk_add_f32 v[16:17], v[20:21], v[16:17]
	s_nop 0
	v_cvt_pk_f16_f32 v14, v16, v17
	v_cvt_f32_f16_e32 v16, v15
	v_cvt_f32_f16_sdwa v17, v15 dst_sel:DWORD dst_unused:UNUSED_PAD src0_sel:WORD_1
	v_fma_mix_f32 v3, v13, v13, v3 op_sel_hi:[1,1,0]
	v_pk_add_f32 v[16:17], v[22:23], v[16:17]
	v_fma_mix_f32 v3, v13, v13, v3 op_sel:[1,1,0] op_sel_hi:[1,1,0]
	v_cvt_pk_f16_f32 v15, v16, v17
	v_fma_mix_f32 v3, v14, v14, v3 op_sel_hi:[1,1,0]
	global_store_dwordx4 v[24:25], v[12:15], off
	v_fma_mix_f32 v3, v14, v14, v3 op_sel:[1,1,0] op_sel_hi:[1,1,0]
	s_nop 0
	v_fma_mix_f32 v3, v15, v15, v3 op_sel_hi:[1,1,0]
	s_nop 0
	v_fma_mix_f32 v3, v15, v15, v3 op_sel:[1,1,0] op_sel_hi:[1,1,0]
	s_nop 1
	v_add_f32_dpp v3, v3, v3 quad_perm:[1,0,3,2] row_mask:0xf bank_mask:0xf
	s_waitcnt lgkmcnt(0)
	s_nop 1
	v_add_f32_dpp v3, v3, v3 quad_perm:[2,3,0,1] row_mask:0xf bank_mask:0xf
	s_waitcnt lgkmcnt(0)
	s_nop 1
	v_add_f32_dpp v3, v3, v3 row_half_mirror row_mask:0xf bank_mask:0xf
	s_waitcnt lgkmcnt(0)
	s_nop 1
	v_mov_b32_dpp v11, v3 row_mirror row_mask:0xf bank_mask:0xf
	s_and_saveexec_b64 s[42:43], vcc
	s_cbranch_execz .LBB0_41
	v_lshlrev_b64 v[4:5], 6, v[4:5]
	s_waitcnt lgkmcnt(0)
	v_add_f32_e32 v34, v3, v11
	v_lshl_add_u64 v[4:5], s[36:37], 0, v[4:5]
	global_store_dwordx2 v[4:5], v[34:35], off
.LBB0_41:
	s_or_b64 exec, exec, s[42:43]
	v_add_u32_e32 v4, 32, v2
	v_ashrrev_i32_e32 v5, 31, v4
	v_lshlrev_b64 v[12:13], 11, v[4:5]
	v_lshl_add_u64 v[24:25], v[0:1], 0, v[12:13]
	global_load_dwordx4 v[12:15], v[24:25], off
	ds_read_b128 v[16:19], v10 offset:16896
	ds_read_b128 v[20:23], v10 offset:16912
	s_waitcnt vmcnt(0)
	v_cvt_f32_f16_e32 v26, v12
	v_cvt_f32_f16_sdwa v27, v12 dst_sel:DWORD dst_unused:UNUSED_PAD src0_sel:WORD_1
	s_waitcnt lgkmcnt(1)
	v_pk_add_f32 v[16:17], v[16:17], v[26:27]
	s_nop 0
	v_cvt_pk_f16_f32 v12, v16, v17
	v_cvt_f32_f16_e32 v16, v13
	v_cvt_f32_f16_sdwa v17, v13 dst_sel:DWORD dst_unused:UNUSED_PAD src0_sel:WORD_1
	v_cvt_f32_f16_sdwa v3, v12 dst_sel:DWORD dst_unused:UNUSED_PAD src0_sel:WORD_1
	v_pk_add_f32 v[16:17], v[18:19], v[16:17]
	s_nop 0
	v_cvt_pk_f16_f32 v13, v16, v17
	v_cvt_f32_f16_e32 v16, v14
	v_cvt_f32_f16_sdwa v17, v14 dst_sel:DWORD dst_unused:UNUSED_PAD src0_sel:WORD_1
	v_mul_f32_e32 v3, v3, v3
	v_fma_mix_f32 v3, v12, v12, v3 op_sel_hi:[1,1,0]
	s_waitcnt lgkmcnt(0)
	v_pk_add_f32 v[16:17], v[20:21], v[16:17]
	s_nop 0
	v_cvt_pk_f16_f32 v14, v16, v17
	v_cvt_f32_f16_e32 v16, v15
	v_cvt_f32_f16_sdwa v17, v15 dst_sel:DWORD dst_unused:UNUSED_PAD src0_sel:WORD_1
	v_fma_mix_f32 v3, v13, v13, v3 op_sel_hi:[1,1,0]
	v_pk_add_f32 v[16:17], v[22:23], v[16:17]
	v_fma_mix_f32 v3, v13, v13, v3 op_sel:[1,1,0] op_sel_hi:[1,1,0]
	v_cvt_pk_f16_f32 v15, v16, v17
	v_fma_mix_f32 v3, v14, v14, v3 op_sel_hi:[1,1,0]
	global_store_dwordx4 v[24:25], v[12:15], off
	v_fma_mix_f32 v3, v14, v14, v3 op_sel:[1,1,0] op_sel_hi:[1,1,0]
	s_nop 0
	v_fma_mix_f32 v3, v15, v15, v3 op_sel_hi:[1,1,0]
	s_nop 0
	v_fma_mix_f32 v3, v15, v15, v3 op_sel:[1,1,0] op_sel_hi:[1,1,0]
	s_nop 1
	v_add_f32_dpp v3, v3, v3 quad_perm:[1,0,3,2] row_mask:0xf bank_mask:0xf
	s_waitcnt lgkmcnt(0)
	s_nop 1
	v_add_f32_dpp v3, v3, v3 quad_perm:[2,3,0,1] row_mask:0xf bank_mask:0xf
	s_waitcnt lgkmcnt(0)
	s_nop 1
	v_add_f32_dpp v3, v3, v3 row_half_mirror row_mask:0xf bank_mask:0xf
	s_waitcnt lgkmcnt(0)
	s_nop 1
	v_mov_b32_dpp v11, v3 row_mirror row_mask:0xf bank_mask:0xf
	s_and_saveexec_b64 s[42:43], vcc
	s_cbranch_execz .LBB0_43
	v_lshlrev_b64 v[4:5], 6, v[4:5]
	s_waitcnt lgkmcnt(0)
	v_add_f32_e32 v34, v3, v11
	v_lshl_add_u64 v[4:5], s[36:37], 0, v[4:5]
	global_store_dwordx2 v[4:5], v[34:35], off
; DI float hlo(unsigned u) { return h2f((bf16_t)(u & 0xffffu)); }
; DI float hhi(unsigned u) { return h2f((bf16_t)(u >> 16)); }
; DI void ph_res(KP p, const bf16_t* A, int K, const bf16_t* Wt, const float* xin, char* smem, bool dry) {
;     ...
;         for (int i = 0; i < 8; ++i) {
;             const int row = (tt >> 4) + 16 * i;
;             const float4 lo = *(const float4*)(stg + row * 132 + c8 * 8), hi = *(const float4*)(stg + row * 132 + c8 * 8 + 4);
;             uint4* gp = (uint4*)(xb + (size_t)row * DM + c8 * 8);
;             const uint4 xv = *gp;
;             uint4 nv;
;             nv.x = pack2h(hlo(xv.x) + lo.x, hhi(xv.x) + lo.y); nv.y = pack2h(hlo(xv.y) + lo.z, hhi(xv.y) + lo.w);
;             nv.z = pack2h(hlo(xv.z) + hi.x, hhi(xv.z) + hi.y); nv.w = pack2h(hlo(xv.w) + hi.z, hhi(xv.w) + hi.w);
;             *gp = nv;
;             float s0 = hlo(nv.x), s1 = hhi(nv.x), s2 = hlo(nv.y), s3 = hhi(nv.y), s4 = hlo(nv.z), s5 = hhi(nv.z), s6 = hlo(nv.w), s7 = hhi(nv.w);
;             float sq = s0 * s0 + s1 * s1 + s2 * s2 + s3 * s3 + s4 * s4 + s5 * s5 + s6 * s6 + s7 * s7;
;             sq += __shfl_xor(sq, 1); sq += __shfl_xor(sq, 2); sq += __shfl_xor(sq, 4); sq += __shfl_xor(sq, 8);
;             if (c8 == 0) { float2 pv; pv.x = sq; pv.y = 0.f; *(float2*)(part + (size_t)row * 16) = pv; }
.LBB0_43:
	s_or_b64 exec, exec, s[42:43]
	v_add_u32_e32 v4, 48, v2
	v_ashrrev_i32_e32 v5, 31, v4
	v_lshlrev_b64 v[12:13], 11, v[4:5]
	v_lshl_add_u64 v[24:25], v[0:1], 0, v[12:13]
	global_load_dwordx4 v[12:15], v[24:25], off
	ds_read_b128 v[16:19], v10 offset:25344
	ds_read_b128 v[20:23], v10 offset:25360
	s_waitcnt vmcnt(0)
	v_cvt_f32_f16_e32 v26, v12
	v_cvt_f32_f16_sdwa v27, v12 dst_sel:DWORD dst_unused:UNUSED_PAD src0_sel:WORD_1
	s_waitcnt lgkmcnt(1)
	v_pk_add_f32 v[16:17], v[16:17], v[26:27]
	s_nop 0
	v_cvt_pk_f16_f32 v12, v16, v17
	v_cvt_f32_f16_e32 v16, v13
	v_cvt_f32_f16_sdwa v17, v13 dst_sel:DWORD dst_unused:UNUSED_PAD src0_sel:WORD_1
	v_cvt_f32_f16_sdwa v3, v12 dst_sel:DWORD dst_unused:UNUSED_PAD src0_sel:WORD_1
	v_pk_add_f32 v[16:17], v[18:19], v[16:17]
	s_nop 0
	v_cvt_pk_f16_f32 v13, v16, v17
	v_cvt_f32_f16_e32 v16, v14
	v_cvt_f32_f16_sdwa v17, v14 dst_sel:DWORD dst_unused:UNUSED_PAD src0_sel:WORD_1
	v_mul_f32_e32 v3, v3, v3
	v_fma_mix_f32 v3, v12, v12, v3 op_sel_hi:[1,1,0]
	s_waitcnt lgkmcnt(0)
	v_pk_add_f32 v[16:17], v[20:21], v[16:17]
	s_nop 0
	v_cvt_pk_f16_f32 v14, v16, v17
	v_cvt_f32_f16_e32 v16, v15
	v_cvt_f32_f16_sdwa v17, v15 dst_sel:DWORD dst_unused:UNUSED_PAD src0_sel:WORD_1
	v_fma_mix_f32 v3, v13, v13, v3 op_sel_hi:[1,1,0]
	v_pk_add_f32 v[16:17], v[22:23], v[16:17]
	v_fma_mix_f32 v3, v13, v13, v3 op_sel:[1,1,0] op_sel_hi:[1,1,0]
	v_cvt_pk_f16_f32 v15, v16, v17
	v_fma_mix_f32 v3, v14, v14, v3 op_sel_hi:[1,1,0]
	global_store_dwordx4 v[24:25], v[12:15], off
	v_fma_mix_f32 v3, v14, v14, v3 op_sel:[1,1,0] op_sel_hi:[1,1,0]
	s_nop 0
	v_fma_mix_f32 v3, v15, v15, v3 op_sel_hi:[1,1,0]
	s_nop 0
	v_fma_mix_f32 v3, v15, v15, v3 op_sel:[1,1,0] op_sel_hi:[1,1,0]
	s_nop 1
	v_add_f32_dpp v3, v3, v3 quad_perm:[1,0,3,2] row_mask:0xf bank_mask:0xf
	s_waitcnt lgkmcnt(0)
	s_nop 1
	v_add_f32_dpp v3, v3, v3 quad_perm:[2,3,0,1] row_mask:0xf bank_mask:0xf
	s_waitcnt lgkmcnt(0)
	s_nop 1
	v_add_f32_dpp v3, v3, v3 row_half_mirror row_mask:0xf bank_mask:0xf
	s_waitcnt lgkmcnt(0)
	s_nop 1
	v_mov_b32_dpp v11, v3 row_mirror row_mask:0xf bank_mask:0xf
	s_and_saveexec_b64 s[42:43], vcc
	s_cbranch_execz .LBB0_45
	v_lshlrev_b64 v[4:5], 6, v[4:5]
	s_waitcnt lgkmcnt(0)
	v_add_f32_e32 v34, v3, v11
	v_lshl_add_u64 v[4:5], s[36:37], 0, v[4:5]
	global_store_dwordx2 v[4:5], v[34:35], off
.LBB0_45:
	s_or_b64 exec, exec, s[42:43]
	v_add_u32_e32 v4, 64, v2
	v_ashrrev_i32_e32 v5, 31, v4
	v_lshlrev_b64 v[12:13], 11, v[4:5]
	v_lshl_add_u64 v[24:25], v[0:1], 0, v[12:13]
	global_load_dwordx4 v[12:15], v[24:25], off
	ds_read_b128 v[16:19], v10 offset:33792
	ds_read_b128 v[20:23], v10 offset:33808
	s_waitcnt vmcnt(0)
	v_cvt_f32_f16_e32 v26, v12
	v_cvt_f32_f16_sdwa v27, v12 dst_sel:DWORD dst_unused:UNUSED_PAD src0_sel:WORD_1
	s_waitcnt lgkmcnt(1)
	v_pk_add_f32 v[16:17], v[16:17], v[26:27]
	s_nop 0
	v_cvt_pk_f16_f32 v12, v16, v17
	v_cvt_f32_f16_e32 v16, v13
	v_cvt_f32_f16_sdwa v17, v13 dst_sel:DWORD dst_unused:UNUSED_PAD src0_sel:WORD_1
	v_cvt_f32_f16_sdwa v3, v12 dst_sel:DWORD dst_unused:UNUSED_PAD src0_sel:WORD_1
	v_pk_add_f32 v[16:17], v[18:19], v[16:17]
	s_nop 0
	v_cvt_pk_f16_f32 v13, v16, v17
	v_cvt_f32_f16_e32 v16, v14
	v_cvt_f32_f16_sdwa v17, v14 dst_sel:DWORD dst_unused:UNUSED_PAD src0_sel:WORD_1
	v_mul_f32_e32 v3, v3, v3
	v_fma_mix_f32 v3, v12, v12, v3 op_sel_hi:[1,1,0]
	s_waitcnt lgkmcnt(0)
	v_pk_add_f32 v[16:17], v[20:21], v[16:17]
	s_nop 0
	v_cvt_pk_f16_f32 v14, v16, v17
	v_cvt_f32_f16_e32 v16, v15
	v_cvt_f32_f16_sdwa v17, v15 dst_sel:DWORD dst_unused:UNUSED_PAD src0_sel:WORD_1
	v_fma_mix_f32 v3, v13, v13, v3 op_sel_hi:[1,1,0]
	v_pk_add_f32 v[16:17], v[22:23], v[16:17]
	v_fma_mix_f32 v3, v13, v13, v3 op_sel:[1,1,0] op_sel_hi:[1,1,0]
	v_cvt_pk_f16_f32 v15, v16, v17
	v_fma_mix_f32 v3, v14, v14, v3 op_sel_hi:[1,1,0]
	global_store_dwordx4 v[24:25], v[12:15], off
	v_fma_mix_f32 v3, v14, v14, v3 op_sel:[1,1,0] op_sel_hi:[1,1,0]
	s_nop 0
	v_fma_mix_f32 v3, v15, v15, v3 op_sel_hi:[1,1,0]
	s_nop 0
	v_fma_mix_f32 v3, v15, v15, v3 op_sel:[1,1,0] op_sel_hi:[1,1,0]
	s_nop 1
	v_add_f32_dpp v3, v3, v3 quad_perm:[1,0,3,2] row_mask:0xf bank_mask:0xf
	s_waitcnt lgkmcnt(0)
	s_nop 1
	v_add_f32_dpp v3, v3, v3 quad_perm:[2,3,0,1] row_mask:0xf bank_mask:0xf
	s_waitcnt lgkmcnt(0)
	s_nop 1
	v_add_f32_dpp v3, v3, v3 row_half_mirror row_mask:0xf bank_mask:0xf
	s_waitcnt lgkmcnt(0)
	s_nop 1
	v_mov_b32_dpp v11, v3 row_mirror row_mask:0xf bank_mask:0xf
	s_and_saveexec_b64 s[42:43], vcc
	s_cbranch_execz .LBB0_47
	v_lshlrev_b64 v[4:5], 6, v[4:5]
	s_waitcnt lgkmcnt(0)
	v_add_f32_e32 v34, v3, v11
	v_lshl_add_u64 v[4:5], s[36:37], 0, v[4:5]
	global_store_dwordx2 v[4:5], v[34:35], off
; DI float hlo(unsigned u) { return h2f((bf16_t)(u & 0xffffu)); }
; DI float hhi(unsigned u) { return h2f((bf16_t)(u >> 16)); }
; DI void ph_res(KP p, const bf16_t* A, int K, const bf16_t* Wt, const float* xin, char* smem, bool dry) {
;     ...
;         for (int i = 0; i < 8; ++i) {
;             const int row = (tt >> 4) + 16 * i;
;             const float4 lo = *(const float4*)(stg + row * 132 + c8 * 8), hi = *(const float4*)(stg + row * 132 + c8 * 8 + 4);
;             uint4* gp = (uint4*)(xb + (size_t)row * DM + c8 * 8);
;             const uint4 xv = *gp;
;             uint4 nv;
;             nv.x = pack2h(hlo(xv.x) + lo.x, hhi(xv.x) + lo.y); nv.y = pack2h(hlo(xv.y) + lo.z, hhi(xv.y) + lo.w);
;             nv.z = pack2h(hlo(xv.z) + hi.x, hhi(xv.z) + hi.y); nv.w = pack2h(hlo(xv.w) + hi.z, hhi(xv.w) + hi.w);
;             *gp = nv;
;             float s0 = hlo(nv.x), s1 = hhi(nv.x), s2 = hlo(nv.y), s3 = hhi(nv.y), s4 = hlo(nv.z), s5 = hhi(nv.z), s6 = hlo(nv.w), s7 = hhi(nv.w);
;             float sq = s0 * s0 + s1 * s1 + s2 * s2 + s3 * s3 + s4 * s4 + s5 * s5 + s6 * s6 + s7 * s7;
;             sq += __shfl_xor(sq, 1); sq += __shfl_xor(sq, 2); sq += __shfl_xor(sq, 4); sq += __shfl_xor(sq, 8);
;             if (c8 == 0) { float2 pv; pv.x = sq; pv.y = 0.f; *(float2*)(part + (size_t)row * 16) = pv; }
.LBB0_47:
	s_or_b64 exec, exec, s[42:43]
	v_add_u32_e32 v4, 0x50, v2
	v_ashrrev_i32_e32 v5, 31, v4
	v_lshlrev_b64 v[12:13], 11, v[4:5]
	v_lshl_add_u64 v[24:25], v[0:1], 0, v[12:13]
	global_load_dwordx4 v[12:15], v[24:25], off
	ds_read_b128 v[16:19], v10 offset:42240
	ds_read_b128 v[20:23], v10 offset:42256
	s_waitcnt vmcnt(0)
	v_cvt_f32_f16_e32 v26, v12
	v_cvt_f32_f16_sdwa v27, v12 dst_sel:DWORD dst_unused:UNUSED_PAD src0_sel:WORD_1
	s_waitcnt lgkmcnt(1)
	v_pk_add_f32 v[16:17], v[16:17], v[26:27]
	s_nop 0
	v_cvt_pk_f16_f32 v12, v16, v17
	v_cvt_f32_f16_e32 v16, v13
	v_cvt_f32_f16_sdwa v17, v13 dst_sel:DWORD dst_unused:UNUSED_PAD src0_sel:WORD_1
	v_cvt_f32_f16_sdwa v3, v12 dst_sel:DWORD dst_unused:UNUSED_PAD src0_sel:WORD_1
	v_pk_add_f32 v[16:17], v[18:19], v[16:17]
	s_nop 0
	v_cvt_pk_f16_f32 v13, v16, v17
	v_cvt_f32_f16_e32 v16, v14
	v_cvt_f32_f16_sdwa v17, v14 dst_sel:DWORD dst_unused:UNUSED_PAD src0_sel:WORD_1
	v_mul_f32_e32 v3, v3, v3
	v_fma_mix_f32 v3, v12, v12, v3 op_sel_hi:[1,1,0]
	s_waitcnt lgkmcnt(0)
	v_pk_add_f32 v[16:17], v[20:21], v[16:17]
	s_nop 0
	v_cvt_pk_f16_f32 v14, v16, v17
	v_cvt_f32_f16_e32 v16, v15
	v_cvt_f32_f16_sdwa v17, v15 dst_sel:DWORD dst_unused:UNUSED_PAD src0_sel:WORD_1
	v_fma_mix_f32 v3, v13, v13, v3 op_sel_hi:[1,1,0]
	v_pk_add_f32 v[16:17], v[22:23], v[16:17]
	v_fma_mix_f32 v3, v13, v13, v3 op_sel:[1,1,0] op_sel_hi:[1,1,0]
	v_cvt_pk_f16_f32 v15, v16, v17
	v_fma_mix_f32 v3, v14, v14, v3 op_sel_hi:[1,1,0]
	global_store_dwordx4 v[24:25], v[12:15], off
	v_fma_mix_f32 v3, v14, v14, v3 op_sel:[1,1,0] op_sel_hi:[1,1,0]
	s_nop 0
	v_fma_mix_f32 v3, v15, v15, v3 op_sel_hi:[1,1,0]
	s_nop 0
	v_fma_mix_f32 v3, v15, v15, v3 op_sel:[1,1,0] op_sel_hi:[1,1,0]
	s_nop 1
	v_add_f32_dpp v3, v3, v3 quad_perm:[1,0,3,2] row_mask:0xf bank_mask:0xf
	s_waitcnt lgkmcnt(0)
	s_nop 1
	v_add_f32_dpp v3, v3, v3 quad_perm:[2,3,0,1] row_mask:0xf bank_mask:0xf
	s_waitcnt lgkmcnt(0)
	s_nop 1
	v_add_f32_dpp v3, v3, v3 row_half_mirror row_mask:0xf bank_mask:0xf
	s_waitcnt lgkmcnt(0)
	s_nop 1
	v_mov_b32_dpp v11, v3 row_mirror row_mask:0xf bank_mask:0xf
	s_and_saveexec_b64 s[42:43], vcc
	s_cbranch_execz .LBB0_49
	v_lshlrev_b64 v[4:5], 6, v[4:5]
	s_waitcnt lgkmcnt(0)
	v_add_f32_e32 v34, v3, v11
	v_lshl_add_u64 v[4:5], s[36:37], 0, v[4:5]
	global_store_dwordx2 v[4:5], v[34:35], off
.LBB0_49:
	s_or_b64 exec, exec, s[42:43]
	v_add_u32_e32 v4, 0x60, v2
	v_ashrrev_i32_e32 v5, 31, v4
	v_lshlrev_b64 v[12:13], 11, v[4:5]
	v_lshl_add_u64 v[24:25], v[0:1], 0, v[12:13]
	global_load_dwordx4 v[12:15], v[24:25], off
	ds_read_b128 v[16:19], v10 offset:50688
	ds_read_b128 v[20:23], v10 offset:50704
	s_waitcnt vmcnt(0)
	v_cvt_f32_f16_e32 v26, v12
	v_cvt_f32_f16_sdwa v27, v12 dst_sel:DWORD dst_unused:UNUSED_PAD src0_sel:WORD_1
	s_waitcnt lgkmcnt(1)
	v_pk_add_f32 v[16:17], v[16:17], v[26:27]
	s_nop 0
	v_cvt_pk_f16_f32 v12, v16, v17
	v_cvt_f32_f16_e32 v16, v13
	v_cvt_f32_f16_sdwa v17, v13 dst_sel:DWORD dst_unused:UNUSED_PAD src0_sel:WORD_1
	v_cvt_f32_f16_sdwa v3, v12 dst_sel:DWORD dst_unused:UNUSED_PAD src0_sel:WORD_1
	v_pk_add_f32 v[16:17], v[18:19], v[16:17]
	s_nop 0
	v_cvt_pk_f16_f32 v13, v16, v17
	v_cvt_f32_f16_e32 v16, v14
	v_cvt_f32_f16_sdwa v17, v14 dst_sel:DWORD dst_unused:UNUSED_PAD src0_sel:WORD_1
	v_mul_f32_e32 v3, v3, v3
	v_fma_mix_f32 v3, v12, v12, v3 op_sel_hi:[1,1,0]
	s_waitcnt lgkmcnt(0)
	v_pk_add_f32 v[16:17], v[20:21], v[16:17]
	s_nop 0
	v_cvt_pk_f16_f32 v14, v16, v17
	v_cvt_f32_f16_e32 v16, v15
	v_cvt_f32_f16_sdwa v17, v15 dst_sel:DWORD dst_unused:UNUSED_PAD src0_sel:WORD_1
	v_fma_mix_f32 v3, v13, v13, v3 op_sel_hi:[1,1,0]
	v_pk_add_f32 v[16:17], v[22:23], v[16:17]
	v_fma_mix_f32 v3, v13, v13, v3 op_sel:[1,1,0] op_sel_hi:[1,1,0]
	v_cvt_pk_f16_f32 v15, v16, v17
	v_fma_mix_f32 v3, v14, v14, v3 op_sel_hi:[1,1,0]
	global_store_dwordx4 v[24:25], v[12:15], off
	v_fma_mix_f32 v3, v14, v14, v3 op_sel:[1,1,0] op_sel_hi:[1,1,0]
	s_nop 0
	v_fma_mix_f32 v3, v15, v15, v3 op_sel_hi:[1,1,0]
	s_nop 0
	v_fma_mix_f32 v3, v15, v15, v3 op_sel:[1,1,0] op_sel_hi:[1,1,0]
	s_nop 1
	v_add_f32_dpp v3, v3, v3 quad_perm:[1,0,3,2] row_mask:0xf bank_mask:0xf
	s_waitcnt lgkmcnt(0)
	s_nop 1
	v_add_f32_dpp v3, v3, v3 quad_perm:[2,3,0,1] row_mask:0xf bank_mask:0xf
	s_waitcnt lgkmcnt(0)
	s_nop 1
	v_add_f32_dpp v3, v3, v3 row_half_mirror row_mask:0xf bank_mask:0xf
	s_waitcnt lgkmcnt(0)
	s_nop 1
	v_mov_b32_dpp v11, v3 row_mirror row_mask:0xf bank_mask:0xf
	s_and_saveexec_b64 s[42:43], vcc
	s_cbranch_execz .LBB0_51
	v_lshlrev_b64 v[4:5], 6, v[4:5]
	s_waitcnt lgkmcnt(0)
	v_add_f32_e32 v34, v3, v11
	v_lshl_add_u64 v[4:5], s[36:37], 0, v[4:5]
	global_store_dwordx2 v[4:5], v[34:35], off
.LBB0_51:
	s_or_b64 exec, exec, s[42:43]
	v_add_u32_e32 v2, 0x70, v2
	v_ashrrev_i32_e32 v3, 31, v2
	v_lshlrev_b64 v[4:5], 11, v[2:3]
	v_lshl_add_u64 v[0:1], v[0:1], 0, v[4:5]
	global_load_dwordx4 v[12:15], v[0:1], off
	ds_read_b128 v[16:19], v10 offset:59136
	ds_read_b128 v[20:23], v10 offset:59152
	s_waitcnt vmcnt(0)
	v_cvt_f32_f16_e32 v4, v12
	v_cvt_f32_f16_sdwa v5, v12 dst_sel:DWORD dst_unused:UNUSED_PAD src0_sel:WORD_1
	s_waitcnt lgkmcnt(1)
	v_pk_add_f32 v[4:5], v[16:17], v[4:5]
	s_nop 0
	v_cvt_pk_f16_f32 v10, v4, v5
	v_cvt_f32_f16_e32 v4, v13
	v_cvt_f32_f16_sdwa v5, v13 dst_sel:DWORD dst_unused:UNUSED_PAD src0_sel:WORD_1
	v_pk_add_f32 v[4:5], v[18:19], v[4:5]
	s_nop 0
	v_cvt_pk_f16_f32 v11, v4, v5
	v_cvt_f32_f16_e32 v4, v14
	v_cvt_f32_f16_sdwa v5, v14 dst_sel:DWORD dst_unused:UNUSED_PAD src0_sel:WORD_1
	s_waitcnt lgkmcnt(0)
	v_pk_add_f32 v[4:5], v[20:21], v[4:5]
	s_nop 0
	v_cvt_pk_f16_f32 v12, v4, v5
	v_cvt_f32_f16_e32 v4, v15
	v_cvt_f32_f16_sdwa v5, v15 dst_sel:DWORD dst_unused:UNUSED_PAD src0_sel:WORD_1
	v_pk_add_f32 v[4:5], v[22:23], v[4:5]
	s_nop 0
	v_cvt_pk_f16_f32 v13, v4, v5
	global_store_dwordx4 v[0:1], v[10:13], off
	v_cvt_f32_f16_sdwa v0, v10 dst_sel:DWORD dst_unused:UNUSED_PAD src0_sel:WORD_1
	v_mul_f32_e32 v0, v0, v0
	v_fma_mix_f32 v0, v10, v10, v0 op_sel_hi:[1,1,0]
	s_nop 0
	v_fma_mix_f32 v0, v11, v11, v0 op_sel_hi:[1,1,0]
	s_nop 0
	v_fma_mix_f32 v0, v11, v11, v0 op_sel:[1,1,0] op_sel_hi:[1,1,0]
	s_nop 0
	v_fma_mix_f32 v0, v12, v12, v0 op_sel_hi:[1,1,0]
	s_nop 0
	v_fma_mix_f32 v0, v12, v12, v0 op_sel:[1,1,0] op_sel_hi:[1,1,0]
	s_nop 0
	v_fma_mix_f32 v0, v13, v13, v0 op_sel_hi:[1,1,0]
	s_nop 0
	v_fma_mix_f32 v0, v13, v13, v0 op_sel:[1,1,0] op_sel_hi:[1,1,0]
	s_nop 1
	v_add_f32_dpp v0, v0, v0 quad_perm:[1,0,3,2] row_mask:0xf bank_mask:0xf
	s_waitcnt lgkmcnt(0)
	s_nop 1
	v_add_f32_dpp v0, v0, v0 quad_perm:[2,3,0,1] row_mask:0xf bank_mask:0xf
	s_waitcnt lgkmcnt(0)
	s_nop 1
	v_add_f32_dpp v0, v0, v0 row_half_mirror row_mask:0xf bank_mask:0xf
	s_waitcnt lgkmcnt(0)
	s_nop 1
	v_mov_b32_dpp v1, v0 row_mirror row_mask:0xf bank_mask:0xf
	s_and_saveexec_b64 s[42:43], vcc
	s_cbranch_execz .LBB0_30
	s_waitcnt lgkmcnt(0)
	v_add_f32_e32 v34, v0, v1
	v_lshlrev_b64 v[0:1], 6, v[2:3]
	v_lshl_add_u64 v[0:1], s[36:37], 0, v[0:1]
	global_store_dwordx2 v[0:1], v[34:35], off
	s_branch .LBB0_30

; DI float hlo(unsigned u) { return h2f((bf16_t)(u & 0xffffu)); }
; DI float hhi(unsigned u) { return h2f((bf16_t)(u >> 16)); }
; DI int crow(int r, int h) { return (r & 3) + 8 * (r >> 2) + 4 * h; }
; DI void ph_res(KP p, const bf16_t* A, int K, const bf16_t* Wt, const float* xin, char* smem, bool dry) {
;     ...
; #pragma unroll
;         for (int i = 0; i < 2; ++i)
; #pragma unroll
;             for (int j = 0; j < 2; ++j)
; #pragma unroll
;                 for (int r = 0; r < 16; ++r) stg[(wm * 64 + i * 32 + crow(r, h)) * 132 + wn * 64 + j * 32 + l32] = acc[i][j][r];
;         __syncthreads();
;         bf16_t* xb = (bf16_t*)(p->ws + OFF_XB) + (size_t)(rt * 128) * DM + ct * 128;
;         float* part = (float*)(p->ws + OFF_RSC) + (size_t)(rt * 128) * 16 + ct * 2;
;         const int c8 = tt & 15;
; #pragma unroll
;         for (int i = 0; i < 8; ++i) {
;             const int row = (tt >> 4) + 16 * i;
;             const float4 lo = *(const float4*)(stg + row * 132 + c8 * 8), hi = *(const float4*)(stg + row * 132 + c8 * 8 + 4);
;             uint4* gp = (uint4*)(xb + (size_t)row * DM + c8 * 8);
;             const uint4 xv = *gp;
;             uint4 nv;
;             nv.x = pack2h(hlo(xv.x) + lo.x, hhi(xv.x) + lo.y); nv.y = pack2h(hlo(xv.y) + lo.z, hhi(xv.y) + lo.w);
;             nv.z = pack2h(hlo(xv.z) + hi.x, hhi(xv.z) + hi.y); nv.w = pack2h(hlo(xv.w) + hi.z, hhi(xv.w) + hi.w);
;             *gp = nv;
;             float s0 = hlo(nv.x), s1 = hhi(nv.x), s2 = hlo(nv.y), s3 = hhi(nv.y), s4 = hlo(nv.z), s5 = hhi(nv.z), s6 = hlo(nv.w), s7 = hhi(nv.w);
;             float sq = s0 * s0 + s1 * s1 + s2 * s2 + s3 * s3 + s4 * s4 + s5 * s5 + s6 * s6 + s7 * s7;
;             sq += __shfl_xor(sq, 1); sq += __shfl_xor(sq, 2); sq += __shfl_xor(sq, 4); sq += __shfl_xor(sq, 8);
;             if (c8 == 0) { float2 pv; pv.x = sq; pv.y = 0.f; *(float2*)(part + (size_t)row * 16) = pv; }
.LBB0_98:
	v_mov_b32_e32 v32, v182
	s_ashr_i32 s43, s42, 31
	v_readfirstlane_b32 s12, v32
	s_lshr_b32 s13, s12, 1
	v_and_b32_e32 v33, 31, v32
	s_and_b32 s13, s13, 0xfffffc0
	v_lshrrev_b32_e32 v34, 3, v32
	v_and_or_b32 v34, v34, 4, s13
	v_and_or_b32 v33, s12, 64, v33
	v_mul_lo_u32 v34, v34, s82
	v_lshlrev_b32_e32 v33, 2, v33
	v_add3_u32 v33, 0, v34, v33
	v_add_u32_e32 v34, 0x400, v33
	ds_write2_b32 v33, v52, v36 offset1:32
	ds_write2_b32 v33, v53, v37 offset0:132 offset1:164
	ds_write2_b32 v34, v54, v38 offset0:8 offset1:40
	ds_write2_b32 v34, v55, v39 offset0:140 offset1:172
	v_add_u32_e32 v34, 0x1000, v33
	ds_write2_b32 v34, v56, v40 offset0:32 offset1:64
	ds_write2_b32 v34, v57, v41 offset0:164 offset1:196
	v_add_u32_e32 v34, 0x1400, v33
	ds_write2_b32 v34, v58, v42 offset0:40 offset1:72
	ds_write2_b32 v34, v59, v43 offset0:172 offset1:204
	v_add_u32_e32 v34, 0x2000, v33
	ds_write2_b32 v34, v60, v44 offset0:64 offset1:96
	ds_write2_b32 v34, v61, v45 offset0:196 offset1:228
	v_add_u32_e32 v34, 0x2400, v33
	ds_write2_b32 v34, v62, v46 offset0:72 offset1:104
	ds_write2_b32 v34, v63, v47 offset0:204 offset1:236
	v_add_u32_e32 v34, 0x3000, v33
	ds_write2_b32 v34, v64, v48 offset0:96 offset1:128
	v_add_u32_e32 v34, 0x3200, v33
	ds_write2_b32 v34, v65, v49 offset0:100 offset1:132
	v_add_u32_e32 v34, 0x3400, v33
	ds_write2_b32 v34, v66, v50 offset0:104 offset1:136
	v_add_u32_e32 v34, 0x3600, v33
	ds_write2_b32 v34, v67, v51 offset0:108 offset1:140
	v_add_u32_e32 v34, 0x4000, v33
	ds_write2_b32 v34, v16, v0 offset0:128 offset1:160
	v_add_u32_e32 v0, 0x4400, v33
	ds_write2_b32 v0, v17, v1 offset0:4 offset1:36
	ds_write2_b32 v0, v18, v2 offset0:136 offset1:168
	v_add_u32_e32 v0, 0x4800, v33
	ds_write2_b32 v0, v19, v3 offset0:12 offset1:44
	v_add_u32_e32 v0, 0x5000, v33
	ds_write2_b32 v0, v20, v4 offset0:160 offset1:192
	v_add_u32_e32 v0, 0x5400, v33
	ds_write2_b32 v0, v21, v5 offset0:36 offset1:68
	ds_write2_b32 v0, v22, v6 offset0:168 offset1:200
	v_add_u32_e32 v0, 0x5800, v33
	ds_write2_b32 v0, v23, v7 offset0:44 offset1:76
	v_add_u32_e32 v0, 0x6000, v33
	s_lshl_b64 s[12:13], s[42:43], 11
	ds_write2_b32 v0, v24, v8 offset0:192 offset1:224
	v_add_u32_e32 v0, 0x6400, v33
	s_add_u32 s34, s7, s12
	ds_write2_b32 v0, v25, v9 offset0:68 offset1:100
	ds_write2_b32 v0, v26, v10 offset0:200 offset1:232
	v_add_u32_e32 v0, 0x6800, v33
	s_addc_u32 s35, s8, s13
	s_lshl_b32 s12, s36, 7
	ds_write2_b32 v0, v27, v11 offset0:76 offset1:108
	v_add_u32_e32 v0, 0x7200, v33
	s_ashr_i32 s13, s12, 31
	ds_write2_b32 v0, v28, v12 offset0:96 offset1:128
	v_add_u32_e32 v0, 0x7400, v33
	s_lshl_b64 s[12:13], s[12:13], 1
	ds_write2_b32 v0, v29, v13 offset0:100 offset1:132
	v_add_u32_e32 v0, 0x7600, v33
	s_add_u32 s12, s34, s12
	v_and_b32_e32 v11, 15, v32
	v_ashrrev_i32_e32 v2, 4, v32
	ds_write2_b32 v0, v30, v14 offset0:104 offset1:136
	v_add_u32_e32 v0, 0x7800, v33
	s_addc_u32 s13, s35, s13
	v_lshlrev_b32_e32 v34, 4, v11
	v_ashrrev_i32_e32 v3, 31, v2
	ds_write2_b32 v0, v31, v15 offset0:108 offset1:140
	v_lshl_add_u64 v[0:1], s[12:13], 0, v[34:35]
	v_lshlrev_b64 v[4:5], 11, v[2:3]
	v_lshl_add_u64 v[24:25], v[0:1], 0, v[4:5]
	s_waitcnt lgkmcnt(0)
	s_barrier
	global_load_dwordx4 v[12:15], v[24:25], off
	v_cmp_lt_i32_e32 vcc, v186, v187
	v_lshl_add_u32 v4, v11, 5, 0
	s_lshl_b64 s[12:13], s[42:43], 6
	v_cndmask_b32_e32 v5, v184, v186, vcc
	v_lshlrev_b32_e32 v6, 2, v5
	v_mul_lo_u32 v5, v2, s82
	v_add_u32_e32 v10, v4, v5
	ds_read_b128 v[16:19], v10
	ds_read_b128 v[20:23], v10 offset:16
	v_cmp_lt_i32_e32 vcc, v188, v187
	s_add_u32 s34, s9, s12
	s_addc_u32 s35, s10, s13
	s_lshl_b32 s12, s36, 1
	s_ashr_i32 s13, s12, 31
	s_lshl_b64 s[12:13], s[12:13], 2
	s_add_u32 s36, s34, s12
	s_addc_u32 s37, s35, s13
	s_waitcnt vmcnt(0)
	v_cvt_f32_f16_e32 v4, v12
	v_cvt_f32_f16_sdwa v5, v12 dst_sel:DWORD dst_unused:UNUSED_PAD src0_sel:WORD_1
	v_cvt_f32_f16_e32 v8, v13
	v_cvt_f32_f16_sdwa v9, v13 dst_sel:DWORD dst_unused:UNUSED_PAD src0_sel:WORD_1
	s_waitcnt lgkmcnt(1)
	v_pk_add_f32 v[4:5], v[16:17], v[4:5]
	s_nop 0
	v_cvt_pk_f16_f32 v12, v4, v5
	v_pk_add_f32 v[4:5], v[18:19], v[8:9]
	v_cvt_f32_f16_sdwa v7, v12 dst_sel:DWORD dst_unused:UNUSED_PAD src0_sel:WORD_1
	v_cvt_pk_f16_f32 v13, v4, v5
	v_cvt_f32_f16_e32 v4, v15
	v_cvt_f32_f16_sdwa v5, v15 dst_sel:DWORD dst_unused:UNUSED_PAD src0_sel:WORD_1
	v_cvt_f32_f16_e32 v8, v14
	v_cvt_f32_f16_sdwa v9, v14 dst_sel:DWORD dst_unused:UNUSED_PAD src0_sel:WORD_1
	s_waitcnt lgkmcnt(0)
	v_pk_add_f32 v[4:5], v[22:23], v[4:5]
	s_nop 0
	v_cvt_pk_f16_f32 v15, v4, v5
	v_mul_f32_e32 v4, v7, v7
	v_fma_mix_f32 v4, v12, v12, v4 op_sel_hi:[1,1,0]
	v_pk_add_f32 v[8:9], v[20:21], v[8:9]
	v_fma_mix_f32 v4, v13, v13, v4 op_sel_hi:[1,1,0]
	v_cvt_pk_f16_f32 v14, v8, v9
	v_fma_mix_f32 v4, v13, v13, v4 op_sel:[1,1,0] op_sel_hi:[1,1,0]
	v_cndmask_b32_e32 v7, v184, v188, vcc
	v_fma_mix_f32 v4, v14, v14, v4 op_sel_hi:[1,1,0]
	v_lshlrev_b32_e32 v7, 2, v7
	v_fma_mix_f32 v4, v14, v14, v4 op_sel:[1,1,0] op_sel_hi:[1,1,0]
	v_cmp_lt_i32_e32 vcc, v189, v187
	v_fma_mix_f32 v4, v15, v15, v4 op_sel_hi:[1,1,0]
	global_store_dwordx4 v[24:25], v[12:15], off
	v_fma_mix_f32 v4, v15, v15, v4 op_sel:[1,1,0] op_sel_hi:[1,1,0]
	s_nop 1
	v_add_f32_dpp v4, v4, v4 quad_perm:[1,0,3,2] row_mask:0xf bank_mask:0xf
	v_cndmask_b32_e32 v8, v184, v189, vcc
	v_lshlrev_b32_e32 v8, 2, v8
	v_cmp_lt_i32_e32 vcc, v190, v187
	s_waitcnt lgkmcnt(0)
	s_nop 1
	v_add_f32_dpp v4, v4, v4 quad_perm:[2,3,0,1] row_mask:0xf bank_mask:0xf
	v_cndmask_b32_e32 v9, v184, v190, vcc
	v_lshlrev_b32_e32 v9, 2, v9
	v_cmp_eq_u32_e32 vcc, 0, v11
	s_waitcnt lgkmcnt(0)
	s_nop 1
	v_add_f32_dpp v4, v4, v4 row_half_mirror row_mask:0xf bank_mask:0xf
	s_waitcnt lgkmcnt(0)
	s_nop 1
	v_mov_b32_dpp v5, v4 row_mirror row_mask:0xf bank_mask:0xf
	s_and_saveexec_b64 s[42:43], vcc
	s_cbranch_execz .LBB0_100
	s_waitcnt lgkmcnt(0)
	v_add_f32_e32 v34, v4, v5
	v_lshlrev_b64 v[4:5], 6, v[2:3]
	v_lshl_add_u64 v[4:5], s[36:37], 0, v[4:5]
	global_store_dwordx2 v[4:5], v[34:35], off
